# retention-output units: 31 of the 32 per-row sum-of-squares reductions done with interleaved DPP row rotations instead of serialized LDS bpermute round trips
# speedup vs baseline: 1.0098x; 1.0098x over previous
.LBB0_505:
	s_or_b64 exec, exec, s[40:41]
	v_mul_f32_e32 v97, v33, v33
	v_fmac_f32_e32 v97, v49, v49
	v_mul_f32_e32 v98, v34, v34
	v_fmac_f32_e32 v98, v50, v50
	v_mul_f32_e32 v99, v35, v35
	v_fmac_f32_e32 v99, v51, v51
	v_mul_f32_e32 v100, v36, v36
	v_fmac_f32_e32 v100, v52, v52
	v_mul_f32_e32 v101, v37, v37
	v_fmac_f32_e32 v101, v53, v53
	v_mul_f32_e32 v102, v38, v38
	v_fmac_f32_e32 v102, v54, v54
	v_mul_f32_e32 v103, v39, v39
	v_fmac_f32_e32 v103, v55, v55
	v_mul_f32_e32 v104, v40, v40
	v_fmac_f32_e32 v104, v56, v56
	v_mul_f32_e32 v105, v41, v41
	v_fmac_f32_e32 v105, v57, v57
	v_mul_f32_e32 v106, v42, v42
	v_fmac_f32_e32 v106, v58, v58
	v_mul_f32_e32 v107, v43, v43
	v_fmac_f32_e32 v107, v59, v59
	v_mul_f32_e32 v108, v44, v44
	v_fmac_f32_e32 v108, v60, v60
	v_mul_f32_e32 v109, v45, v45
	v_fmac_f32_e32 v109, v61, v61
	v_mul_f32_e32 v110, v46, v46
	v_fmac_f32_e32 v110, v62, v62
	v_mul_f32_e32 v111, v47, v47
	v_fmac_f32_e32 v111, v63, v63
	v_mul_f32_e32 v112, v0, v0
	v_fmac_f32_e32 v112, v16, v16
	v_mul_f32_e32 v113, v1, v1
	v_fmac_f32_e32 v113, v17, v17
	v_mul_f32_e32 v114, v2, v2
	v_fmac_f32_e32 v114, v18, v18
	v_mul_f32_e32 v115, v3, v3
	v_fmac_f32_e32 v115, v19, v19
	v_mul_f32_e32 v116, v4, v4
	v_fmac_f32_e32 v116, v20, v20
	v_mul_f32_e32 v117, v5, v5
	v_fmac_f32_e32 v117, v21, v21
	v_mul_f32_e32 v118, v6, v6
	v_fmac_f32_e32 v118, v22, v22
	v_mul_f32_e32 v119, v7, v7
	v_fmac_f32_e32 v119, v23, v23
	v_mul_f32_e32 v120, v8, v8
	v_fmac_f32_e32 v120, v24, v24
	v_mul_f32_e32 v121, v9, v9
	v_fmac_f32_e32 v121, v25, v25
	v_mul_f32_e32 v122, v10, v10
	v_fmac_f32_e32 v122, v26, v26
	v_mul_f32_e32 v123, v11, v11
	v_fmac_f32_e32 v123, v27, v27
	v_mul_f32_e32 v124, v12, v12
	v_fmac_f32_e32 v124, v28, v28
	v_mul_f32_e32 v125, v13, v13
	v_fmac_f32_e32 v125, v29, v29
	v_mul_f32_e32 v126, v14, v14
	v_fmac_f32_e32 v126, v30, v30
	v_add_f32_dpp v97, v97, v97 row_ror:8 row_mask:0xf bank_mask:0xf
	v_add_f32_dpp v98, v98, v98 row_ror:8 row_mask:0xf bank_mask:0xf
	v_add_f32_dpp v99, v99, v99 row_ror:8 row_mask:0xf bank_mask:0xf
	v_add_f32_dpp v100, v100, v100 row_ror:8 row_mask:0xf bank_mask:0xf
	v_add_f32_dpp v101, v101, v101 row_ror:8 row_mask:0xf bank_mask:0xf
	v_add_f32_dpp v102, v102, v102 row_ror:8 row_mask:0xf bank_mask:0xf
	v_add_f32_dpp v103, v103, v103 row_ror:8 row_mask:0xf bank_mask:0xf
	v_add_f32_dpp v104, v104, v104 row_ror:8 row_mask:0xf bank_mask:0xf
	v_add_f32_dpp v105, v105, v105 row_ror:8 row_mask:0xf bank_mask:0xf
	v_add_f32_dpp v106, v106, v106 row_ror:8 row_mask:0xf bank_mask:0xf
	v_add_f32_dpp v107, v107, v107 row_ror:8 row_mask:0xf bank_mask:0xf
	v_add_f32_dpp v108, v108, v108 row_ror:8 row_mask:0xf bank_mask:0xf
	v_add_f32_dpp v109, v109, v109 row_ror:8 row_mask:0xf bank_mask:0xf
	v_add_f32_dpp v110, v110, v110 row_ror:8 row_mask:0xf bank_mask:0xf
	v_add_f32_dpp v111, v111, v111 row_ror:8 row_mask:0xf bank_mask:0xf
	v_add_f32_dpp v112, v112, v112 row_ror:8 row_mask:0xf bank_mask:0xf
	v_add_f32_dpp v113, v113, v113 row_ror:8 row_mask:0xf bank_mask:0xf
	v_add_f32_dpp v114, v114, v114 row_ror:8 row_mask:0xf bank_mask:0xf
	v_add_f32_dpp v115, v115, v115 row_ror:8 row_mask:0xf bank_mask:0xf
	v_add_f32_dpp v116, v116, v116 row_ror:8 row_mask:0xf bank_mask:0xf
	v_add_f32_dpp v117, v117, v117 row_ror:8 row_mask:0xf bank_mask:0xf
	v_add_f32_dpp v118, v118, v118 row_ror:8 row_mask:0xf bank_mask:0xf
	v_add_f32_dpp v119, v119, v119 row_ror:8 row_mask:0xf bank_mask:0xf
	v_add_f32_dpp v120, v120, v120 row_ror:8 row_mask:0xf bank_mask:0xf
	v_add_f32_dpp v121, v121, v121 row_ror:8 row_mask:0xf bank_mask:0xf
	v_add_f32_dpp v122, v122, v122 row_ror:8 row_mask:0xf bank_mask:0xf
	v_add_f32_dpp v123, v123, v123 row_ror:8 row_mask:0xf bank_mask:0xf
	v_add_f32_dpp v124, v124, v124 row_ror:8 row_mask:0xf bank_mask:0xf
	v_add_f32_dpp v125, v125, v125 row_ror:8 row_mask:0xf bank_mask:0xf
	v_add_f32_dpp v126, v126, v126 row_ror:8 row_mask:0xf bank_mask:0xf
	v_add_f32_dpp v97, v97, v97 row_ror:4 row_mask:0xf bank_mask:0xf
	v_add_f32_dpp v98, v98, v98 row_ror:4 row_mask:0xf bank_mask:0xf
	v_add_f32_dpp v99, v99, v99 row_ror:4 row_mask:0xf bank_mask:0xf
	v_add_f32_dpp v100, v100, v100 row_ror:4 row_mask:0xf bank_mask:0xf
	v_add_f32_dpp v101, v101, v101 row_ror:4 row_mask:0xf bank_mask:0xf
	v_add_f32_dpp v102, v102, v102 row_ror:4 row_mask:0xf bank_mask:0xf
	v_add_f32_dpp v103, v103, v103 row_ror:4 row_mask:0xf bank_mask:0xf
	v_add_f32_dpp v104, v104, v104 row_ror:4 row_mask:0xf bank_mask:0xf
	v_add_f32_dpp v105, v105, v105 row_ror:4 row_mask:0xf bank_mask:0xf
	v_add_f32_dpp v106, v106, v106 row_ror:4 row_mask:0xf bank_mask:0xf
	v_add_f32_dpp v107, v107, v107 row_ror:4 row_mask:0xf bank_mask:0xf
	v_add_f32_dpp v108, v108, v108 row_ror:4 row_mask:0xf bank_mask:0xf
	v_add_f32_dpp v109, v109, v109 row_ror:4 row_mask:0xf bank_mask:0xf
	v_add_f32_dpp v110, v110, v110 row_ror:4 row_mask:0xf bank_mask:0xf
	v_add_f32_dpp v111, v111, v111 row_ror:4 row_mask:0xf bank_mask:0xf
	v_add_f32_dpp v112, v112, v112 row_ror:4 row_mask:0xf bank_mask:0xf
	v_add_f32_dpp v113, v113, v113 row_ror:4 row_mask:0xf bank_mask:0xf
	v_add_f32_dpp v114, v114, v114 row_ror:4 row_mask:0xf bank_mask:0xf
	v_add_f32_dpp v115, v115, v115 row_ror:4 row_mask:0xf bank_mask:0xf
	v_add_f32_dpp v116, v116, v116 row_ror:4 row_mask:0xf bank_mask:0xf
	v_add_f32_dpp v117, v117, v117 row_ror:4 row_mask:0xf bank_mask:0xf
	v_add_f32_dpp v118, v118, v118 row_ror:4 row_mask:0xf bank_mask:0xf
	v_add_f32_dpp v119, v119, v119 row_ror:4 row_mask:0xf bank_mask:0xf
	v_add_f32_dpp v120, v120, v120 row_ror:4 row_mask:0xf bank_mask:0xf
	v_add_f32_dpp v121, v121, v121 row_ror:4 row_mask:0xf bank_mask:0xf
	v_add_f32_dpp v122, v122, v122 row_ror:4 row_mask:0xf bank_mask:0xf
	v_add_f32_dpp v123, v123, v123 row_ror:4 row_mask:0xf bank_mask:0xf
	v_add_f32_dpp v124, v124, v124 row_ror:4 row_mask:0xf bank_mask:0xf
	v_add_f32_dpp v125, v125, v125 row_ror:4 row_mask:0xf bank_mask:0xf
	v_add_f32_dpp v126, v126, v126 row_ror:4 row_mask:0xf bank_mask:0xf
	v_add_f32_dpp v97, v97, v97 row_ror:2 row_mask:0xf bank_mask:0xf
	v_add_f32_dpp v98, v98, v98 row_ror:2 row_mask:0xf bank_mask:0xf
	v_add_f32_dpp v99, v99, v99 row_ror:2 row_mask:0xf bank_mask:0xf
	v_add_f32_dpp v100, v100, v100 row_ror:2 row_mask:0xf bank_mask:0xf
	v_add_f32_dpp v101, v101, v101 row_ror:2 row_mask:0xf bank_mask:0xf
	v_add_f32_dpp v102, v102, v102 row_ror:2 row_mask:0xf bank_mask:0xf
	v_add_f32_dpp v103, v103, v103 row_ror:2 row_mask:0xf bank_mask:0xf
	v_add_f32_dpp v104, v104, v104 row_ror:2 row_mask:0xf bank_mask:0xf
	v_add_f32_dpp v105, v105, v105 row_ror:2 row_mask:0xf bank_mask:0xf
	v_add_f32_dpp v106, v106, v106 row_ror:2 row_mask:0xf bank_mask:0xf
	v_add_f32_dpp v107, v107, v107 row_ror:2 row_mask:0xf bank_mask:0xf
	v_add_f32_dpp v108, v108, v108 row_ror:2 row_mask:0xf bank_mask:0xf
	v_add_f32_dpp v109, v109, v109 row_ror:2 row_mask:0xf bank_mask:0xf
	v_add_f32_dpp v110, v110, v110 row_ror:2 row_mask:0xf bank_mask:0xf
	v_add_f32_dpp v111, v111, v111 row_ror:2 row_mask:0xf bank_mask:0xf
	v_add_f32_dpp v112, v112, v112 row_ror:2 row_mask:0xf bank_mask:0xf
	v_add_f32_dpp v113, v113, v113 row_ror:2 row_mask:0xf bank_mask:0xf
	v_add_f32_dpp v114, v114, v114 row_ror:2 row_mask:0xf bank_mask:0xf
	v_add_f32_dpp v115, v115, v115 row_ror:2 row_mask:0xf bank_mask:0xf
	v_add_f32_dpp v116, v116, v116 row_ror:2 row_mask:0xf bank_mask:0xf
	v_add_f32_dpp v117, v117, v117 row_ror:2 row_mask:0xf bank_mask:0xf
	v_add_f32_dpp v118, v118, v118 row_ror:2 row_mask:0xf bank_mask:0xf
	v_add_f32_dpp v119, v119, v119 row_ror:2 row_mask:0xf bank_mask:0xf
	v_add_f32_dpp v120, v120, v120 row_ror:2 row_mask:0xf bank_mask:0xf
	v_add_f32_dpp v121, v121, v121 row_ror:2 row_mask:0xf bank_mask:0xf
	v_add_f32_dpp v122, v122, v122 row_ror:2 row_mask:0xf bank_mask:0xf
	v_add_f32_dpp v123, v123, v123 row_ror:2 row_mask:0xf bank_mask:0xf
	v_add_f32_dpp v124, v124, v124 row_ror:2 row_mask:0xf bank_mask:0xf
	v_add_f32_dpp v125, v125, v125 row_ror:2 row_mask:0xf bank_mask:0xf
	v_add_f32_dpp v126, v126, v126 row_ror:2 row_mask:0xf bank_mask:0xf
	v_add_f32_dpp v97, v97, v97 row_ror:1 row_mask:0xf bank_mask:0xf
	v_add_f32_dpp v98, v98, v98 row_ror:1 row_mask:0xf bank_mask:0xf
	v_add_f32_dpp v99, v99, v99 row_ror:1 row_mask:0xf bank_mask:0xf
	v_add_f32_dpp v100, v100, v100 row_ror:1 row_mask:0xf bank_mask:0xf
	v_add_f32_dpp v101, v101, v101 row_ror:1 row_mask:0xf bank_mask:0xf
	v_add_f32_dpp v102, v102, v102 row_ror:1 row_mask:0xf bank_mask:0xf
	v_add_f32_dpp v103, v103, v103 row_ror:1 row_mask:0xf bank_mask:0xf
	v_add_f32_dpp v104, v104, v104 row_ror:1 row_mask:0xf bank_mask:0xf
	v_add_f32_dpp v105, v105, v105 row_ror:1 row_mask:0xf bank_mask:0xf
	v_add_f32_dpp v106, v106, v106 row_ror:1 row_mask:0xf bank_mask:0xf
	v_add_f32_dpp v107, v107, v107 row_ror:1 row_mask:0xf bank_mask:0xf
	v_add_f32_dpp v108, v108, v108 row_ror:1 row_mask:0xf bank_mask:0xf
	v_add_f32_dpp v109, v109, v109 row_ror:1 row_mask:0xf bank_mask:0xf
	v_add_f32_dpp v110, v110, v110 row_ror:1 row_mask:0xf bank_mask:0xf
	v_add_f32_dpp v111, v111, v111 row_ror:1 row_mask:0xf bank_mask:0xf
	v_add_f32_dpp v112, v112, v112 row_ror:1 row_mask:0xf bank_mask:0xf
	v_add_f32_dpp v113, v113, v113 row_ror:1 row_mask:0xf bank_mask:0xf
	v_add_f32_dpp v114, v114, v114 row_ror:1 row_mask:0xf bank_mask:0xf
	v_add_f32_dpp v115, v115, v115 row_ror:1 row_mask:0xf bank_mask:0xf
	v_add_f32_dpp v116, v116, v116 row_ror:1 row_mask:0xf bank_mask:0xf
	v_add_f32_dpp v117, v117, v117 row_ror:1 row_mask:0xf bank_mask:0xf
	v_add_f32_dpp v118, v118, v118 row_ror:1 row_mask:0xf bank_mask:0xf
	v_add_f32_dpp v119, v119, v119 row_ror:1 row_mask:0xf bank_mask:0xf
	v_add_f32_dpp v120, v120, v120 row_ror:1 row_mask:0xf bank_mask:0xf
	v_add_f32_dpp v121, v121, v121 row_ror:1 row_mask:0xf bank_mask:0xf
	v_add_f32_dpp v122, v122, v122 row_ror:1 row_mask:0xf bank_mask:0xf
	v_add_f32_dpp v123, v123, v123 row_ror:1 row_mask:0xf bank_mask:0xf
	v_add_f32_dpp v124, v124, v124 row_ror:1 row_mask:0xf bank_mask:0xf
	v_add_f32_dpp v125, v125, v125 row_ror:1 row_mask:0xf bank_mask:0xf
	v_add_f32_dpp v126, v126, v126 row_ror:1 row_mask:0xf bank_mask:0xf
	v_add_f32_dpp v97, v97, v97 row_bcast:15 row_mask:0xa bank_mask:0xf
	v_add_f32_dpp v98, v98, v98 row_bcast:15 row_mask:0xa bank_mask:0xf
	v_add_f32_dpp v99, v99, v99 row_bcast:15 row_mask:0xa bank_mask:0xf
	v_add_f32_dpp v100, v100, v100 row_bcast:15 row_mask:0xa bank_mask:0xf
	v_add_f32_dpp v101, v101, v101 row_bcast:15 row_mask:0xa bank_mask:0xf
	v_add_f32_dpp v102, v102, v102 row_bcast:15 row_mask:0xa bank_mask:0xf
	v_add_f32_dpp v103, v103, v103 row_bcast:15 row_mask:0xa bank_mask:0xf
	v_add_f32_dpp v104, v104, v104 row_bcast:15 row_mask:0xa bank_mask:0xf
	v_add_f32_dpp v105, v105, v105 row_bcast:15 row_mask:0xa bank_mask:0xf
	v_add_f32_dpp v106, v106, v106 row_bcast:15 row_mask:0xa bank_mask:0xf
	v_add_f32_dpp v107, v107, v107 row_bcast:15 row_mask:0xa bank_mask:0xf
	v_add_f32_dpp v108, v108, v108 row_bcast:15 row_mask:0xa bank_mask:0xf
	v_add_f32_dpp v109, v109, v109 row_bcast:15 row_mask:0xa bank_mask:0xf
	v_add_f32_dpp v110, v110, v110 row_bcast:15 row_mask:0xa bank_mask:0xf
	v_add_f32_dpp v111, v111, v111 row_bcast:15 row_mask:0xa bank_mask:0xf
	v_add_f32_dpp v112, v112, v112 row_bcast:15 row_mask:0xa bank_mask:0xf
	v_add_f32_dpp v113, v113, v113 row_bcast:15 row_mask:0xa bank_mask:0xf
	v_add_f32_dpp v114, v114, v114 row_bcast:15 row_mask:0xa bank_mask:0xf
	v_add_f32_dpp v115, v115, v115 row_bcast:15 row_mask:0xa bank_mask:0xf
	v_add_f32_dpp v116, v116, v116 row_bcast:15 row_mask:0xa bank_mask:0xf
	v_add_f32_dpp v117, v117, v117 row_bcast:15 row_mask:0xa bank_mask:0xf
	v_add_f32_dpp v118, v118, v118 row_bcast:15 row_mask:0xa bank_mask:0xf
	v_add_f32_dpp v119, v119, v119 row_bcast:15 row_mask:0xa bank_mask:0xf
	v_add_f32_dpp v120, v120, v120 row_bcast:15 row_mask:0xa bank_mask:0xf
	v_add_f32_dpp v121, v121, v121 row_bcast:15 row_mask:0xa bank_mask:0xf
	v_add_f32_dpp v122, v122, v122 row_bcast:15 row_mask:0xa bank_mask:0xf
	v_add_f32_dpp v123, v123, v123 row_bcast:15 row_mask:0xa bank_mask:0xf
	v_add_f32_dpp v124, v124, v124 row_bcast:15 row_mask:0xa bank_mask:0xf
	v_add_f32_dpp v125, v125, v125 row_bcast:15 row_mask:0xa bank_mask:0xf
	v_add_f32_dpp v126, v126, v126 row_bcast:15 row_mask:0xa bank_mask:0xf
	s_waitcnt lgkmcnt(0)
	s_mov_b64 s[40:41], exec
	s_mov_b32 exec_lo, 0x10000
	s_mov_b32 exec_hi, 0x10000
	ds_write_b32 v65, v97 offset:8
	ds_write_b32 v65, v98 offset:16
	ds_write_b32 v65, v99 offset:24
	ds_write_b32 v65, v100 offset:64
	ds_write_b32 v65, v101 offset:72
	ds_write_b32 v65, v102 offset:80
	ds_write_b32 v65, v103 offset:88
	ds_write_b32 v65, v104 offset:128
	ds_write_b32 v65, v105 offset:136
	ds_write_b32 v65, v106 offset:144
	ds_write_b32 v65, v107 offset:152
	ds_write_b32 v65, v108 offset:192
	ds_write_b32 v65, v109 offset:200
	ds_write_b32 v65, v110 offset:208
	ds_write_b32 v65, v111 offset:216
	ds_write_b32 v65, v112 offset:256
	ds_write_b32 v65, v113 offset:264
	ds_write_b32 v65, v114 offset:272
	ds_write_b32 v65, v115 offset:280
	ds_write_b32 v65, v116 offset:320
	ds_write_b32 v65, v117 offset:328
	ds_write_b32 v65, v118 offset:336
	ds_write_b32 v65, v119 offset:344
	ds_write_b32 v65, v120 offset:384
	ds_write_b32 v65, v121 offset:392
	ds_write_b32 v65, v122 offset:400
	ds_write_b32 v65, v123 offset:408
	ds_write_b32 v65, v124 offset:448
	ds_write_b32 v65, v125 offset:456
	ds_write_b32 v65, v126 offset:464
	s_mov_b64 exec, s[40:41]

.LBB0_639:
	s_or_b64 exec, exec, s[2:3]
	v_mul_f32_e32 v97, v33, v33
	v_fmac_f32_e32 v97, v49, v49
	v_mul_f32_e32 v98, v34, v34
	v_fmac_f32_e32 v98, v50, v50
	v_mul_f32_e32 v99, v35, v35
	v_fmac_f32_e32 v99, v51, v51
	v_mul_f32_e32 v100, v36, v36
	v_fmac_f32_e32 v100, v52, v52
	v_mul_f32_e32 v101, v37, v37
	v_fmac_f32_e32 v101, v53, v53
	v_mul_f32_e32 v102, v38, v38
	v_fmac_f32_e32 v102, v54, v54
	v_mul_f32_e32 v103, v39, v39
	v_fmac_f32_e32 v103, v55, v55
	v_mul_f32_e32 v104, v40, v40
	v_fmac_f32_e32 v104, v56, v56
	v_mul_f32_e32 v105, v41, v41
	v_fmac_f32_e32 v105, v57, v57
	v_mul_f32_e32 v106, v42, v42
	v_fmac_f32_e32 v106, v58, v58
	v_mul_f32_e32 v107, v43, v43
	v_fmac_f32_e32 v107, v59, v59
	v_mul_f32_e32 v108, v44, v44
	v_fmac_f32_e32 v108, v60, v60
	v_mul_f32_e32 v109, v45, v45
	v_fmac_f32_e32 v109, v61, v61
	v_mul_f32_e32 v110, v46, v46
	v_fmac_f32_e32 v110, v62, v62
	v_mul_f32_e32 v111, v47, v47
	v_fmac_f32_e32 v111, v63, v63
	v_mul_f32_e32 v112, v0, v0
	v_fmac_f32_e32 v112, v16, v16
	v_mul_f32_e32 v113, v1, v1
	v_fmac_f32_e32 v113, v17, v17
	v_mul_f32_e32 v114, v2, v2
	v_fmac_f32_e32 v114, v18, v18
	v_mul_f32_e32 v115, v3, v3
	v_fmac_f32_e32 v115, v19, v19
	v_mul_f32_e32 v116, v4, v4
	v_fmac_f32_e32 v116, v20, v20
	v_mul_f32_e32 v117, v5, v5
	v_fmac_f32_e32 v117, v21, v21
	v_mul_f32_e32 v118, v6, v6
	v_fmac_f32_e32 v118, v22, v22
	v_mul_f32_e32 v119, v7, v7
	v_fmac_f32_e32 v119, v23, v23
	v_mul_f32_e32 v120, v8, v8
	v_fmac_f32_e32 v120, v24, v24
	v_mul_f32_e32 v121, v9, v9
	v_fmac_f32_e32 v121, v25, v25
	v_mul_f32_e32 v122, v10, v10
	v_fmac_f32_e32 v122, v26, v26
	v_mul_f32_e32 v123, v11, v11
	v_fmac_f32_e32 v123, v27, v27
	v_mul_f32_e32 v124, v12, v12
	v_fmac_f32_e32 v124, v28, v28
	v_mul_f32_e32 v125, v13, v13
	v_fmac_f32_e32 v125, v29, v29
	v_mul_f32_e32 v126, v14, v14
	v_fmac_f32_e32 v126, v30, v30
	v_add_f32_dpp v97, v97, v97 row_ror:8 row_mask:0xf bank_mask:0xf
	v_add_f32_dpp v98, v98, v98 row_ror:8 row_mask:0xf bank_mask:0xf
	v_add_f32_dpp v99, v99, v99 row_ror:8 row_mask:0xf bank_mask:0xf
	v_add_f32_dpp v100, v100, v100 row_ror:8 row_mask:0xf bank_mask:0xf
	v_add_f32_dpp v101, v101, v101 row_ror:8 row_mask:0xf bank_mask:0xf
	v_add_f32_dpp v102, v102, v102 row_ror:8 row_mask:0xf bank_mask:0xf
	v_add_f32_dpp v103, v103, v103 row_ror:8 row_mask:0xf bank_mask:0xf
	v_add_f32_dpp v104, v104, v104 row_ror:8 row_mask:0xf bank_mask:0xf
	v_add_f32_dpp v105, v105, v105 row_ror:8 row_mask:0xf bank_mask:0xf
	v_add_f32_dpp v106, v106, v106 row_ror:8 row_mask:0xf bank_mask:0xf
	v_add_f32_dpp v107, v107, v107 row_ror:8 row_mask:0xf bank_mask:0xf
	v_add_f32_dpp v108, v108, v108 row_ror:8 row_mask:0xf bank_mask:0xf
	v_add_f32_dpp v109, v109, v109 row_ror:8 row_mask:0xf bank_mask:0xf
	v_add_f32_dpp v110, v110, v110 row_ror:8 row_mask:0xf bank_mask:0xf
	v_add_f32_dpp v111, v111, v111 row_ror:8 row_mask:0xf bank_mask:0xf
	v_add_f32_dpp v112, v112, v112 row_ror:8 row_mask:0xf bank_mask:0xf
	v_add_f32_dpp v113, v113, v113 row_ror:8 row_mask:0xf bank_mask:0xf
	v_add_f32_dpp v114, v114, v114 row_ror:8 row_mask:0xf bank_mask:0xf
	v_add_f32_dpp v115, v115, v115 row_ror:8 row_mask:0xf bank_mask:0xf
	v_add_f32_dpp v116, v116, v116 row_ror:8 row_mask:0xf bank_mask:0xf
	v_add_f32_dpp v117, v117, v117 row_ror:8 row_mask:0xf bank_mask:0xf
	v_add_f32_dpp v118, v118, v118 row_ror:8 row_mask:0xf bank_mask:0xf
	v_add_f32_dpp v119, v119, v119 row_ror:8 row_mask:0xf bank_mask:0xf
	v_add_f32_dpp v120, v120, v120 row_ror:8 row_mask:0xf bank_mask:0xf
	v_add_f32_dpp v121, v121, v121 row_ror:8 row_mask:0xf bank_mask:0xf
	v_add_f32_dpp v122, v122, v122 row_ror:8 row_mask:0xf bank_mask:0xf
	v_add_f32_dpp v123, v123, v123 row_ror:8 row_mask:0xf bank_mask:0xf
	v_add_f32_dpp v124, v124, v124 row_ror:8 row_mask:0xf bank_mask:0xf
	v_add_f32_dpp v125, v125, v125 row_ror:8 row_mask:0xf bank_mask:0xf
	v_add_f32_dpp v126, v126, v126 row_ror:8 row_mask:0xf bank_mask:0xf
	v_add_f32_dpp v97, v97, v97 row_ror:4 row_mask:0xf bank_mask:0xf
	v_add_f32_dpp v98, v98, v98 row_ror:4 row_mask:0xf bank_mask:0xf
	v_add_f32_dpp v99, v99, v99 row_ror:4 row_mask:0xf bank_mask:0xf
	v_add_f32_dpp v100, v100, v100 row_ror:4 row_mask:0xf bank_mask:0xf
	v_add_f32_dpp v101, v101, v101 row_ror:4 row_mask:0xf bank_mask:0xf
	v_add_f32_dpp v102, v102, v102 row_ror:4 row_mask:0xf bank_mask:0xf
	v_add_f32_dpp v103, v103, v103 row_ror:4 row_mask:0xf bank_mask:0xf
	v_add_f32_dpp v104, v104, v104 row_ror:4 row_mask:0xf bank_mask:0xf
	v_add_f32_dpp v105, v105, v105 row_ror:4 row_mask:0xf bank_mask:0xf
	v_add_f32_dpp v106, v106, v106 row_ror:4 row_mask:0xf bank_mask:0xf
	v_add_f32_dpp v107, v107, v107 row_ror:4 row_mask:0xf bank_mask:0xf
	v_add_f32_dpp v108, v108, v108 row_ror:4 row_mask:0xf bank_mask:0xf
	v_add_f32_dpp v109, v109, v109 row_ror:4 row_mask:0xf bank_mask:0xf
	v_add_f32_dpp v110, v110, v110 row_ror:4 row_mask:0xf bank_mask:0xf
	v_add_f32_dpp v111, v111, v111 row_ror:4 row_mask:0xf bank_mask:0xf
	v_add_f32_dpp v112, v112, v112 row_ror:4 row_mask:0xf bank_mask:0xf
	v_add_f32_dpp v113, v113, v113 row_ror:4 row_mask:0xf bank_mask:0xf
	v_add_f32_dpp v114, v114, v114 row_ror:4 row_mask:0xf bank_mask:0xf
	v_add_f32_dpp v115, v115, v115 row_ror:4 row_mask:0xf bank_mask:0xf
	v_add_f32_dpp v116, v116, v116 row_ror:4 row_mask:0xf bank_mask:0xf
	v_add_f32_dpp v117, v117, v117 row_ror:4 row_mask:0xf bank_mask:0xf
	v_add_f32_dpp v118, v118, v118 row_ror:4 row_mask:0xf bank_mask:0xf
	v_add_f32_dpp v119, v119, v119 row_ror:4 row_mask:0xf bank_mask:0xf
	v_add_f32_dpp v120, v120, v120 row_ror:4 row_mask:0xf bank_mask:0xf
	v_add_f32_dpp v121, v121, v121 row_ror:4 row_mask:0xf bank_mask:0xf
	v_add_f32_dpp v122, v122, v122 row_ror:4 row_mask:0xf bank_mask:0xf
	v_add_f32_dpp v123, v123, v123 row_ror:4 row_mask:0xf bank_mask:0xf
	v_add_f32_dpp v124, v124, v124 row_ror:4 row_mask:0xf bank_mask:0xf
	v_add_f32_dpp v125, v125, v125 row_ror:4 row_mask:0xf bank_mask:0xf
	v_add_f32_dpp v126, v126, v126 row_ror:4 row_mask:0xf bank_mask:0xf
	v_add_f32_dpp v97, v97, v97 row_ror:2 row_mask:0xf bank_mask:0xf
	v_add_f32_dpp v98, v98, v98 row_ror:2 row_mask:0xf bank_mask:0xf
	v_add_f32_dpp v99, v99, v99 row_ror:2 row_mask:0xf bank_mask:0xf
	v_add_f32_dpp v100, v100, v100 row_ror:2 row_mask:0xf bank_mask:0xf
	v_add_f32_dpp v101, v101, v101 row_ror:2 row_mask:0xf bank_mask:0xf
	v_add_f32_dpp v102, v102, v102 row_ror:2 row_mask:0xf bank_mask:0xf
	v_add_f32_dpp v103, v103, v103 row_ror:2 row_mask:0xf bank_mask:0xf
	v_add_f32_dpp v104, v104, v104 row_ror:2 row_mask:0xf bank_mask:0xf
	v_add_f32_dpp v105, v105, v105 row_ror:2 row_mask:0xf bank_mask:0xf
	v_add_f32_dpp v106, v106, v106 row_ror:2 row_mask:0xf bank_mask:0xf
	v_add_f32_dpp v107, v107, v107 row_ror:2 row_mask:0xf bank_mask:0xf
	v_add_f32_dpp v108, v108, v108 row_ror:2 row_mask:0xf bank_mask:0xf
	v_add_f32_dpp v109, v109, v109 row_ror:2 row_mask:0xf bank_mask:0xf
	v_add_f32_dpp v110, v110, v110 row_ror:2 row_mask:0xf bank_mask:0xf
	v_add_f32_dpp v111, v111, v111 row_ror:2 row_mask:0xf bank_mask:0xf
	v_add_f32_dpp v112, v112, v112 row_ror:2 row_mask:0xf bank_mask:0xf
	v_add_f32_dpp v113, v113, v113 row_ror:2 row_mask:0xf bank_mask:0xf
	v_add_f32_dpp v114, v114, v114 row_ror:2 row_mask:0xf bank_mask:0xf
	v_add_f32_dpp v115, v115, v115 row_ror:2 row_mask:0xf bank_mask:0xf
	v_add_f32_dpp v116, v116, v116 row_ror:2 row_mask:0xf bank_mask:0xf
	v_add_f32_dpp v117, v117, v117 row_ror:2 row_mask:0xf bank_mask:0xf
	v_add_f32_dpp v118, v118, v118 row_ror:2 row_mask:0xf bank_mask:0xf
	v_add_f32_dpp v119, v119, v119 row_ror:2 row_mask:0xf bank_mask:0xf
	v_add_f32_dpp v120, v120, v120 row_ror:2 row_mask:0xf bank_mask:0xf
	v_add_f32_dpp v121, v121, v121 row_ror:2 row_mask:0xf bank_mask:0xf
	v_add_f32_dpp v122, v122, v122 row_ror:2 row_mask:0xf bank_mask:0xf
	v_add_f32_dpp v123, v123, v123 row_ror:2 row_mask:0xf bank_mask:0xf
	v_add_f32_dpp v124, v124, v124 row_ror:2 row_mask:0xf bank_mask:0xf
	v_add_f32_dpp v125, v125, v125 row_ror:2 row_mask:0xf bank_mask:0xf
	v_add_f32_dpp v126, v126, v126 row_ror:2 row_mask:0xf bank_mask:0xf
	v_add_f32_dpp v97, v97, v97 row_ror:1 row_mask:0xf bank_mask:0xf
	v_add_f32_dpp v98, v98, v98 row_ror:1 row_mask:0xf bank_mask:0xf
	v_add_f32_dpp v99, v99, v99 row_ror:1 row_mask:0xf bank_mask:0xf
	v_add_f32_dpp v100, v100, v100 row_ror:1 row_mask:0xf bank_mask:0xf
	v_add_f32_dpp v101, v101, v101 row_ror:1 row_mask:0xf bank_mask:0xf
	v_add_f32_dpp v102, v102, v102 row_ror:1 row_mask:0xf bank_mask:0xf
	v_add_f32_dpp v103, v103, v103 row_ror:1 row_mask:0xf bank_mask:0xf
	v_add_f32_dpp v104, v104, v104 row_ror:1 row_mask:0xf bank_mask:0xf
	v_add_f32_dpp v105, v105, v105 row_ror:1 row_mask:0xf bank_mask:0xf
	v_add_f32_dpp v106, v106, v106 row_ror:1 row_mask:0xf bank_mask:0xf
	v_add_f32_dpp v107, v107, v107 row_ror:1 row_mask:0xf bank_mask:0xf
	v_add_f32_dpp v108, v108, v108 row_ror:1 row_mask:0xf bank_mask:0xf
	v_add_f32_dpp v109, v109, v109 row_ror:1 row_mask:0xf bank_mask:0xf
	v_add_f32_dpp v110, v110, v110 row_ror:1 row_mask:0xf bank_mask:0xf
	v_add_f32_dpp v111, v111, v111 row_ror:1 row_mask:0xf bank_mask:0xf
	v_add_f32_dpp v112, v112, v112 row_ror:1 row_mask:0xf bank_mask:0xf
	v_add_f32_dpp v113, v113, v113 row_ror:1 row_mask:0xf bank_mask:0xf
	v_add_f32_dpp v114, v114, v114 row_ror:1 row_mask:0xf bank_mask:0xf
	v_add_f32_dpp v115, v115, v115 row_ror:1 row_mask:0xf bank_mask:0xf
	v_add_f32_dpp v116, v116, v116 row_ror:1 row_mask:0xf bank_mask:0xf
	v_add_f32_dpp v117, v117, v117 row_ror:1 row_mask:0xf bank_mask:0xf
	v_add_f32_dpp v118, v118, v118 row_ror:1 row_mask:0xf bank_mask:0xf
	v_add_f32_dpp v119, v119, v119 row_ror:1 row_mask:0xf bank_mask:0xf
	v_add_f32_dpp v120, v120, v120 row_ror:1 row_mask:0xf bank_mask:0xf
	v_add_f32_dpp v121, v121, v121 row_ror:1 row_mask:0xf bank_mask:0xf
	v_add_f32_dpp v122, v122, v122 row_ror:1 row_mask:0xf bank_mask:0xf
	v_add_f32_dpp v123, v123, v123 row_ror:1 row_mask:0xf bank_mask:0xf
	v_add_f32_dpp v124, v124, v124 row_ror:1 row_mask:0xf bank_mask:0xf
	v_add_f32_dpp v125, v125, v125 row_ror:1 row_mask:0xf bank_mask:0xf
	v_add_f32_dpp v126, v126, v126 row_ror:1 row_mask:0xf bank_mask:0xf
	v_add_f32_dpp v97, v97, v97 row_bcast:15 row_mask:0xa bank_mask:0xf
	v_add_f32_dpp v98, v98, v98 row_bcast:15 row_mask:0xa bank_mask:0xf
	v_add_f32_dpp v99, v99, v99 row_bcast:15 row_mask:0xa bank_mask:0xf
	v_add_f32_dpp v100, v100, v100 row_bcast:15 row_mask:0xa bank_mask:0xf
	v_add_f32_dpp v101, v101, v101 row_bcast:15 row_mask:0xa bank_mask:0xf
	v_add_f32_dpp v102, v102, v102 row_bcast:15 row_mask:0xa bank_mask:0xf
	v_add_f32_dpp v103, v103, v103 row_bcast:15 row_mask:0xa bank_mask:0xf
	v_add_f32_dpp v104, v104, v104 row_bcast:15 row_mask:0xa bank_mask:0xf
	v_add_f32_dpp v105, v105, v105 row_bcast:15 row_mask:0xa bank_mask:0xf
	v_add_f32_dpp v106, v106, v106 row_bcast:15 row_mask:0xa bank_mask:0xf
	v_add_f32_dpp v107, v107, v107 row_bcast:15 row_mask:0xa bank_mask:0xf
	v_add_f32_dpp v108, v108, v108 row_bcast:15 row_mask:0xa bank_mask:0xf
	v_add_f32_dpp v109, v109, v109 row_bcast:15 row_mask:0xa bank_mask:0xf
	v_add_f32_dpp v110, v110, v110 row_bcast:15 row_mask:0xa bank_mask:0xf
	v_add_f32_dpp v111, v111, v111 row_bcast:15 row_mask:0xa bank_mask:0xf
	v_add_f32_dpp v112, v112, v112 row_bcast:15 row_mask:0xa bank_mask:0xf
	v_add_f32_dpp v113, v113, v113 row_bcast:15 row_mask:0xa bank_mask:0xf
	v_add_f32_dpp v114, v114, v114 row_bcast:15 row_mask:0xa bank_mask:0xf
	v_add_f32_dpp v115, v115, v115 row_bcast:15 row_mask:0xa bank_mask:0xf
	v_add_f32_dpp v116, v116, v116 row_bcast:15 row_mask:0xa bank_mask:0xf
	v_add_f32_dpp v117, v117, v117 row_bcast:15 row_mask:0xa bank_mask:0xf
	v_add_f32_dpp v118, v118, v118 row_bcast:15 row_mask:0xa bank_mask:0xf
	v_add_f32_dpp v119, v119, v119 row_bcast:15 row_mask:0xa bank_mask:0xf
	v_add_f32_dpp v120, v120, v120 row_bcast:15 row_mask:0xa bank_mask:0xf
	v_add_f32_dpp v121, v121, v121 row_bcast:15 row_mask:0xa bank_mask:0xf
	v_add_f32_dpp v122, v122, v122 row_bcast:15 row_mask:0xa bank_mask:0xf
	v_add_f32_dpp v123, v123, v123 row_bcast:15 row_mask:0xa bank_mask:0xf
	v_add_f32_dpp v124, v124, v124 row_bcast:15 row_mask:0xa bank_mask:0xf
	v_add_f32_dpp v125, v125, v125 row_bcast:15 row_mask:0xa bank_mask:0xf
	v_add_f32_dpp v126, v126, v126 row_bcast:15 row_mask:0xa bank_mask:0xf
	s_waitcnt lgkmcnt(0)
	s_mov_b64 s[2:3], exec
	s_mov_b32 exec_lo, 0x10000
	s_mov_b32 exec_hi, 0x10000
	ds_write_b32 v65, v97 offset:8
	ds_write_b32 v65, v98 offset:16
	ds_write_b32 v65, v99 offset:24
	ds_write_b32 v65, v100 offset:64
	ds_write_b32 v65, v101 offset:72
	ds_write_b32 v65, v102 offset:80
	ds_write_b32 v65, v103 offset:88
	ds_write_b32 v65, v104 offset:128
	ds_write_b32 v65, v105 offset:136
	ds_write_b32 v65, v106 offset:144
	ds_write_b32 v65, v107 offset:152
	ds_write_b32 v65, v108 offset:192
	ds_write_b32 v65, v109 offset:200
	ds_write_b32 v65, v110 offset:208
	ds_write_b32 v65, v111 offset:216
	ds_write_b32 v65, v112 offset:256
	ds_write_b32 v65, v113 offset:264
	ds_write_b32 v65, v114 offset:272
	ds_write_b32 v65, v115 offset:280
	ds_write_b32 v65, v116 offset:320
	ds_write_b32 v65, v117 offset:328
	ds_write_b32 v65, v118 offset:336
	ds_write_b32 v65, v119 offset:344
	ds_write_b32 v65, v120 offset:384
	ds_write_b32 v65, v121 offset:392
	ds_write_b32 v65, v122 offset:400
	ds_write_b32 v65, v123 offset:408
	ds_write_b32 v65, v124 offset:448
	ds_write_b32 v65, v125 offset:456
	ds_write_b32 v65, v126 offset:464
	s_mov_b64 exec, s[2:3]
